# FOX attention: P x ones row-sum MFMAs (4 of 20 per tile) replaced by VALU sums interleaved in the PV MFMA gaps; l moved to accumulator layout through LDS at unit end (fp32 sum of unrounded P, as DIFF
# baseline (speedup 1.0000x reference)
.LBB0_834:
	s_setprio 0
	v_mov_b32_e32 v0, v62
	s_lshr_b32 s6, s2, 3
	s_add_i32 s6, s6, 0x10400
	v_permlane32_swap_b32_e32 v62, v0
	v_lshl_add_u32 v2, v136, 2, s6
	v_add_f32_e32 v0, v62, v0
	ds_write_b32 v2, v0
	v_lshl_add_u32 v2, v135, 4, s6
	s_waitcnt lgkmcnt(0)
	ds_read_b128 v[62:65], v2
	ds_read_b128 v[66:69], v2 offset:32
	ds_read_b128 v[70:73], v2 offset:64
	ds_read_b128 v[74:77], v2 offset:96
	s_waitcnt lgkmcnt(0)
	s_lshl_b64 s[6:7], s[74:75], 11
	s_add_u32 s2, s94, s6
	s_nop 1
	v_rcp_f32_e32 v4, v62
	s_addc_u32 s6, s95, s7
	s_add_u32 s2, s2, s3
	s_addc_u32 s3, s6, 0
	v_lshlrev_b32_e32 v0, 1, v136
	v_lshl_add_u64 v[2:3], s[2:3], 0, v[0:1]
	v_lshlrev_b32_e32 v0, 13, v135
	v_rcp_f32_e32 v5, v63
	v_lshl_add_u64 v[2:3], v[2:3], 0, v[0:1]
	v_mul_f32_e32 v0, v32, v4
	v_cvt_pk_bf16_f32 v0, v0, s0
	global_store_short v[2:3], v0, off offset:1024
	v_mul_f32_e32 v0, v16, v4
	v_cvt_pk_bf16_f32 v0, v0, s0
	v_rcp_f32_e32 v6, v64
	global_store_short v[2:3], v0, off offset:1088
	v_mul_f32_e32 v0, v33, v5
	v_cvt_pk_bf16_f32 v0, v0, s0
	global_store_short v[2:3], v0, off offset:3072
	v_mul_f32_e32 v0, v17, v5
	v_cvt_pk_bf16_f32 v0, v0, s0
	s_movk_i32 s2, 0x1000
	v_rcp_f32_e32 v7, v65
	global_store_short v[2:3], v0, off offset:3136
	v_mul_f32_e32 v0, v34, v6
	v_add_co_u32_e32 v4, vcc, s2, v2
	v_cvt_pk_bf16_f32 v0, v0, s0
	s_nop 0
	v_addc_co_u32_e32 v5, vcc, 0, v3, vcc
	global_store_short v[4:5], v0, off offset:1024
	v_mul_f32_e32 v0, v18, v6
	v_cvt_pk_bf16_f32 v0, v0, s0
	v_rcp_f32_e32 v8, v66
	global_store_short v[4:5], v0, off offset:1088
	v_mul_f32_e32 v0, v35, v7
	v_cvt_pk_bf16_f32 v0, v0, s0
	global_store_short v[4:5], v0, off offset:3072
	v_mul_f32_e32 v0, v19, v7
	v_cvt_pk_bf16_f32 v0, v0, s0
	s_movk_i32 s2, 0x4000
	v_rcp_f32_e32 v9, v67
	global_store_short v[4:5], v0, off offset:3136
	v_mul_f32_e32 v0, v36, v8
	v_add_co_u32_e32 v4, vcc, s2, v2
	v_cvt_pk_bf16_f32 v0, v0, s0
	s_nop 0
	v_addc_co_u32_e32 v5, vcc, 0, v3, vcc
	global_store_short v[4:5], v0, off offset:1024
	v_mul_f32_e32 v0, v20, v8
	v_cvt_pk_bf16_f32 v0, v0, s0
	v_rcp_f32_e32 v10, v68
	global_store_short v[4:5], v0, off offset:1088
	v_mul_f32_e32 v0, v37, v9
	v_cvt_pk_bf16_f32 v0, v0, s0
	global_store_short v[4:5], v0, off offset:3072
	v_mul_f32_e32 v0, v21, v9
	v_cvt_pk_bf16_f32 v0, v0, s0
	s_movk_i32 s2, 0x5000
	v_rcp_f32_e32 v11, v69
	global_store_short v[4:5], v0, off offset:3136
	v_mul_f32_e32 v0, v38, v10
	v_add_co_u32_e32 v4, vcc, s2, v2
	v_cvt_pk_bf16_f32 v0, v0, s0
	s_nop 0
	v_addc_co_u32_e32 v5, vcc, 0, v3, vcc
	global_store_short v[4:5], v0, off offset:1024
	v_mul_f32_e32 v0, v22, v10
	v_cvt_pk_bf16_f32 v0, v0, s0
	v_rcp_f32_e32 v12, v70
	global_store_short v[4:5], v0, off offset:1088
	v_mul_f32_e32 v0, v39, v11
	v_cvt_pk_bf16_f32 v0, v0, s0
	global_store_short v[4:5], v0, off offset:3072
	v_mul_f32_e32 v0, v23, v11
	v_cvt_pk_bf16_f32 v0, v0, s0
	s_mov_b32 s2, 0x8000
	v_rcp_f32_e32 v13, v71
	global_store_short v[4:5], v0, off offset:3136
	v_mul_f32_e32 v0, v40, v12
	v_add_co_u32_e32 v4, vcc, s2, v2
	v_cvt_pk_bf16_f32 v0, v0, s0
	s_nop 0
	v_addc_co_u32_e32 v5, vcc, 0, v3, vcc
	global_store_short v[4:5], v0, off offset:1024
	v_mul_f32_e32 v0, v24, v12
	v_cvt_pk_bf16_f32 v0, v0, s0
	v_rcp_f32_e32 v14, v72
	global_store_short v[4:5], v0, off offset:1088
	v_mul_f32_e32 v0, v41, v13
	v_cvt_pk_bf16_f32 v0, v0, s0
	global_store_short v[4:5], v0, off offset:3072
	v_mul_f32_e32 v0, v25, v13
	v_cvt_pk_bf16_f32 v0, v0, s0
	s_mov_b32 s2, 0x9000
	v_rcp_f32_e32 v15, v73
	global_store_short v[4:5], v0, off offset:3136
	v_mul_f32_e32 v0, v42, v14
	v_add_co_u32_e32 v4, vcc, s2, v2
	v_cvt_pk_bf16_f32 v0, v0, s0
	s_nop 0
	v_addc_co_u32_e32 v5, vcc, 0, v3, vcc
	global_store_short v[4:5], v0, off offset:1024
	v_mul_f32_e32 v0, v26, v14
	v_cvt_pk_bf16_f32 v0, v0, s0
	v_rcp_f32_e32 v48, v74
	global_store_short v[4:5], v0, off offset:1088
	v_mul_f32_e32 v0, v43, v15
	v_cvt_pk_bf16_f32 v0, v0, s0
	global_store_short v[4:5], v0, off offset:3072
	v_mul_f32_e32 v0, v27, v15
	v_cvt_pk_bf16_f32 v0, v0, s0
	s_mov_b32 s2, 0xc000
	v_rcp_f32_e32 v49, v75
	global_store_short v[4:5], v0, off offset:3136
	v_mul_f32_e32 v0, v44, v48
	v_add_co_u32_e32 v4, vcc, s2, v2
	v_cvt_pk_bf16_f32 v0, v0, s0
	s_nop 0
	v_addc_co_u32_e32 v5, vcc, 0, v3, vcc
	global_store_short v[4:5], v0, off offset:1024
	v_mul_f32_e32 v0, v28, v48
	v_cvt_pk_bf16_f32 v0, v0, s0
	v_rcp_f32_e32 v50, v76
	global_store_short v[4:5], v0, off offset:1088
	v_mul_f32_e32 v0, v45, v49
	v_cvt_pk_bf16_f32 v0, v0, s0
	global_store_short v[4:5], v0, off offset:3072
	v_mul_f32_e32 v0, v29, v49
	v_cvt_pk_bf16_f32 v0, v0, s0
	s_mov_b32 s2, 0xd000
	v_rcp_f32_e32 v51, v77
	global_store_short v[4:5], v0, off offset:3136
	v_mul_f32_e32 v0, v46, v50
	v_add_co_u32_e32 v2, vcc, s2, v2
	v_cvt_pk_bf16_f32 v0, v0, s0
	s_nop 0
	v_addc_co_u32_e32 v3, vcc, 0, v3, vcc
	global_store_short v[2:3], v0, off offset:1024
	v_mul_f32_e32 v0, v30, v50
	v_cvt_pk_bf16_f32 v0, v0, s0
	global_store_short v[2:3], v0, off offset:1088
	v_mul_f32_e32 v0, v47, v51
	v_cvt_pk_bf16_f32 v0, v0, s0
	global_store_short v[2:3], v0, off offset:3072
	v_mul_f32_e32 v0, v31, v51
	v_cvt_pk_bf16_f32 v0, v0, s0
	global_store_short v[2:3], v0, off offset:3136
	s_waitcnt lgkmcnt(0)
	s_barrier

.LBB0_881:
	v_exp_f32_e32 v80, v80
	v_exp_f32_e32 v81, v81
	v_exp_f32_e32 v82, v82
	v_exp_f32_e32 v83, v83
	v_exp_f32_e32 v84, v84
	v_exp_f32_e32 v85, v85
	v_exp_f32_e32 v86, v86
	v_exp_f32_e32 v87, v87
	v_exp_f32_e32 v88, v88
	v_exp_f32_e32 v89, v89
	v_exp_f32_e32 v90, v90
	v_exp_f32_e32 v91, v91
	v_exp_f32_e32 v92, v92
	v_exp_f32_e32 v93, v93
	v_exp_f32_e32 v94, v94
	v_exp_f32_e32 v95, v95
	v_cvt_pk_bf16_f32 v2, v80, v81
	v_cvt_pk_bf16_f32 v3, v82, v83
	v_cvt_pk_bf16_f32 v4, v84, v85
	v_cvt_pk_bf16_f32 v5, v86, v87
	v_cvt_pk_bf16_f32 v6, v88, v89
	v_cvt_pk_bf16_f32 v7, v90, v91
	v_cvt_pk_bf16_f32 v8, v92, v93
	v_cvt_pk_bf16_f32 v9, v94, v95
	s_waitcnt lgkmcnt(0)
	v_mfma_f32_32x32x16_bf16 v[32:47], v[2:5], v[188:191], v[32:47]
	v_exp_f32_e32 v96, v96
	v_exp_f32_e32 v97, v97
	v_exp_f32_e32 v98, v98
	v_add_f32_e32 v240, v80, v81
	v_add_f32_e32 v241, v82, v83
	v_mfma_f32_32x32x16_bf16 v[32:47], v[6:9], v[192:195], v[32:47]
	v_exp_f32_e32 v99, v99
	v_exp_f32_e32 v100, v100
	v_exp_f32_e32 v101, v101
	v_add_f32_e32 v242, v84, v85
	v_add_f32_e32 v243, v86, v87
	v_mfma_f32_32x32x16_bf16 v[16:31], v[2:5], v[204:207], v[16:31]
	v_exp_f32_e32 v102, v102
	v_exp_f32_e32 v103, v103
	v_exp_f32_e32 v104, v104
	v_add_f32_e32 v244, v88, v89
	v_add_f32_e32 v245, v90, v91
	v_mfma_f32_32x32x16_bf16 v[16:31], v[6:9], v[208:211], v[16:31]
	v_exp_f32_e32 v105, v105
	v_exp_f32_e32 v106, v106
	v_exp_f32_e32 v107, v107
	v_add_f32_e32 v246, v92, v93
	v_add_f32_e32 v247, v94, v95
	v_add_f32_e32 v240, v240, v241
	v_exp_f32_e32 v108, v108
	v_exp_f32_e32 v109, v109
	v_exp_f32_e32 v110, v110
	v_exp_f32_e32 v111, v111
	v_add_f32_e32 v242, v242, v243
	v_add_f32_e32 v244, v244, v245
	v_add_f32_e32 v246, v246, v247
	v_add_f32_e32 v240, v240, v242
	v_add_f32_e32 v244, v244, v246
	v_add_f32_e32 v240, v240, v244
	v_add_f32_e32 v62, v62, v240
	v_cvt_pk_bf16_f32 v10, v96, v97
	v_cvt_pk_bf16_f32 v11, v98, v99
	v_cvt_pk_bf16_f32 v12, v100, v101
	v_cvt_pk_bf16_f32 v13, v102, v103
	v_cvt_pk_bf16_f32 v80, v104, v105
	v_cvt_pk_bf16_f32 v81, v106, v107
	v_cvt_pk_bf16_f32 v82, v108, v109
	v_cvt_pk_bf16_f32 v83, v110, v111
	v_mfma_f32_32x32x16_bf16 v[32:47], v[10:13], v[196:199], v[32:47]
	v_add_f32_e32 v240, v96, v97
	v_add_f32_e32 v241, v98, v99
	v_add_f32_e32 v242, v100, v101
	v_add_f32_e32 v243, v102, v103
	v_mfma_f32_32x32x16_bf16 v[16:31], v[10:13], v[212:215], v[16:31]
	v_add_f32_e32 v244, v104, v105
	v_add_f32_e32 v245, v106, v107
	v_add_f32_e32 v246, v108, v109
	v_add_f32_e32 v247, v110, v111
	v_mfma_f32_32x32x16_bf16 v[32:47], v[80:83], v[200:203], v[32:47]
	v_add_f32_e32 v240, v240, v241
	v_add_f32_e32 v242, v242, v243
	v_add_f32_e32 v244, v244, v245
	v_add_f32_e32 v246, v246, v247
	v_mfma_f32_32x32x16_bf16 v[16:31], v[80:83], v[216:219], v[16:31]
	v_add_f32_e32 v240, v240, v242
	v_add_f32_e32 v244, v244, v246
	v_add_f32_e32 v240, v240, v244
	v_add_f32_e32 v62, v62, v240
	s_or_b64 s[6:7], s[84:85], s[78:79]
	s_and_b64 vcc, exec, s[6:7]
	s_cbranch_vccz .LBB0_884
